# GEMM-out tile order mirrored within each XCD (most recently written MIX panels read first)
# speedup vs baseline: 1.0019x; 1.0019x over previous
;     __device__ __forceinline__ bool next(int i, Unit& u) const { if (i >= 4) return false; u.pm = pm; u.pn = i; return true; }
; #define PG8_STAGE(bufoff, gbase, voff) do { _Pragma("unroll") for (int _i = 0; _i < 2; ++_i) \
;         __builtin_amdgcn_global_load_lds((const unsigned*)((const char*)(gbase) + (voff)[_i]), (LAS unsigned*)(lds + (bufoff) + ldsw + _i * 8192), 16, 0, 0); } while (0)
;     __device__ __forceinline__ bool next(int i, Unit& u) const {
;         const long L = (long)i * G + c; if (L >= nwg) return false;
;         int wgid = (int)L; { const int q = nwg / NXCD, r = nwg % NXCD, xcd = wgid % NXCD, off = wgid / NXCD; wgid = (xcd < r ? xcd * (q + 1) : r * (q + 1) + (xcd - r) * q) + off; }
;         const int nig = WGM * nN, gid = wgid / nig, fm = gid * WGM, gsz = (nM - fm) < WGM ? (nM - fm) : WGM;
;         u.pm = fm + ((wgid % nig) % gsz); u.pn = (wgid % nig) / gsz; return true;
; template <class Epi, class Sched>
; __device__ __forceinline__ void gemm_phase(LAS unsigned char* lds, const Gemm g, const Sched& S, const Epi& E) {
;     ...
;     const char* cA = (const char*)g.A + (size_t)cur.pm * tstep; const char* cB = (const char*)g.Bt + (size_t)cur.pn * tstep;
;     PG8_STAGE(PG8_SB(0, 0), cB, voffB); PG8_STAGE(PG8_SA(0, 0), cA, voffA); PG8_STAGE(PG8_SB(0, 1), cB + hstep, voffB); PG8_STAGE(PG8_SA(0, 1), cA + hstep, voffA);
.LBB0_137:
	s_and_b64 vcc, exec, s[0:1]
	s_cbranch_vccz .LBB0_212
	v_writelane_b32 v254, s86, 63
	s_cmp_gt_i32 s59, 0
	s_mov_b64 s[0:1], -1
	v_writelane_b32 v255, s87, 0
	s_cbranch_scc0 .LBB0_285
	s_cmp_gt_i32 s59, 1
	s_mov_b32 s4, s96
	s_cbranch_scc0 .LBB0_157
	s_waitcnt vmcnt(0)
	v_mov_b32_e32 v8, v225
	s_cmpk_gt_i32 s88, 0x3ff
	s_mov_b64 s[68:69], 0x50000
	v_readfirstlane_b32 s26, v8
	v_readlane_b32 s0, v254, 63
	v_readlane_b32 s1, v255, 0
	s_cbranch_scc1 .LBB0_156
	v_lshlrev_b32_e32 v0, 4, v8
	v_add_u32_e32 v1, 0x2000, v0
	s_mov_b32 s62, s0
	v_readlane_b32 s2, v254, 55
	v_readlane_b32 s0, v254, 59
	v_ashrrev_i32_e32 v2, 31, v1
	v_readlane_b32 s3, v254, 56
	s_add_u32 s27, s2, 0x21f8a000
	v_readlane_b32 s1, v254, 60
	v_lshrrev_b32_e32 v2, 22, v2
	s_addc_u32 s28, s3, 0
	s_mov_b32 s4, s0
	s_ashr_i32 s5, s0, 31
	v_writelane_b32 v254, s0, 59
	v_add_u32_e32 v2, v1, v2
	v_ashrrev_i32_e32 v9, 10, v2
	v_writelane_b32 v254, s1, 60
	s_lshl_b64 s[0:1], s[4:5], 21
	s_add_u32 s0, s2, s0
	v_mul_i32_i24_e32 v2, 0x400, v9
	s_addc_u32 s1, s3, s1
	v_sub_u32_e32 v1, v1, v2
	s_add_u32 s29, s0, 0xa8a000
	v_lshrrev_b32_e32 v2, 4, v1
	s_addc_u32 s30, s1, 0
	v_bitop3_b32 v1, v2, v1, 32 bitop3:0x6c
	s_ashr_i32 s33, s88, 31
	v_ashrrev_i32_e32 v2, 31, v1
	s_lshr_b32 s0, s33, 29
	v_lshrrev_b32_e32 v2, 26, v2
	s_add_i32 s0, s88, s0
	v_add_u32_e32 v2, v1, v2
	s_and_b32 s3, s0, -8
	s_ashr_i32 s1, s26, 6
	v_ashrrev_i32_e32 v10, 6, v2
	v_and_b32_e32 v2, 0xc0, v2
	s_sub_i32 s3, s88, s3
	s_ashr_i32 s2, s26, 8
	s_lshl_b32 s31, s1, 10
	v_sub_u32_e32 v1, v1, v2
	s_lshl_b32 s5, s3, 7
	s_ashr_i32 s0, s0, 3
	v_ashrrev_i16_sdwa v1, v231, sext(v1) dst_sel:DWORD dst_unused:UNUSED_PAD src0_sel:DWORD src1_sel:BYTE_0
	s_mul_i32 s4, s3, 0x81
	s_cmp_lt_i32 s3, 0
	v_bfe_i32 v12, v1, 0, 16
	v_bfe_i32 v1, v8, 27, 1
	s_cselect_b32 s3, s4, s5
	v_lshrrev_b32_e32 v1, 22, v1
	s_add_i32 s0, s3, s0
	s_xor_b32 s0, s0, 0x7f
	v_add_u32_e32 v1, v0, v1
	s_ashr_i32 s3, s0, 31
	v_and_b32_e32 v1, 0xfffffc00, v1
	s_lshr_b32 s3, s3, 27
	v_sub_u32_e32 v0, v0, v1
	s_add_i32 s3, s0, s3
	v_lshrrev_b32_e32 v1, 4, v0
	s_ashr_i32 s4, s3, 5
	s_and_b32 s3, s3, 0xffe0
	v_bitop3_b32 v1, v1, v0, 32 bitop3:0x6c
	v_ashrrev_i32_e32 v0, 31, v0
	s_sub_i32 s3, s0, s3
	v_lshrrev_b32_e32 v0, 26, v0
	s_bfe_i32 s0, s3, 0x80000
	v_add_u32_e32 v0, v1, v0
	s_bfe_u32 s0, s0, 0x3000c
	v_ashrrev_i32_e32 v13, 6, v0
	v_ashrrev_i32_e32 v0, 31, v8
	s_add_i32 s5, s3, s0
	v_lshrrev_b32_e32 v0, 26, v0
	s_bfe_i32 s0, s5, 0x80000
	s_and_b32 s5, s5, 0xf8
	v_add_u32_e32 v0, v8, v0
	s_sub_i32 s3, s3, s5
	v_ashrrev_i32_e32 v14, 6, v0
	s_lshl_b32 s4, s4, 3
	s_sext_i32_i16 s0, s0
	s_sext_i32_i8 s3, s3
	v_lshlrev_b32_e32 v2, 5, v14
	s_lshr_b32 s0, s0, 3
	s_add_i32 s10, s4, s3
	v_lshlrev_b32_e32 v0, 3, v14
	v_and_b32_e32 v15, 32, v2
	v_mul_i32_i24_e32 v2, 64, v13
	s_ashr_i32 s11, s10, 31
	s_bfe_i64 s[6:7], s[0:1], 0x100000
	v_and_b32_e32 v0, 0x1ffff0, v0
	v_sub_u32_e32 v1, v1, v2
	s_lshl_b64 s[4:5], s[10:11], 19
	s_lshl_b64 s[6:7], s[6:7], 19
	v_lshlrev_b32_e32 v3, 3, v9
	v_add_u32_e32 v0, v13, v0
	v_ashrrev_i16_sdwa v1, v231, sext(v1) dst_sel:DWORD dst_unused:UNUSED_PAD src0_sel:DWORD src1_sel:BYTE_0
	s_add_u32 s20, s29, s6
	v_and_b32_e32 v3, 0x1ffff0, v3
	v_lshlrev_b32_e32 v4, 5, v9
	v_lshl_or_b32 v0, v0, 10, v15
	v_bfe_i32 v16, v1, 0, 16
	s_addc_u32 s21, s30, s7
	s_add_i32 s11, s31, 0
	v_add_u32_e32 v3, v10, v3
	v_and_b32_e32 v11, 32, v4
	v_add_lshl_u32 v154, v0, v16, 1
	s_add_i32 m0, s11, 0x10000
	v_lshl_or_b32 v3, v3, 10, v11
	global_load_lds_dwordx4 v154, s[20:21]
	s_add_i32 m0, s11, 0x12000
	v_add_lshl_u32 v128, v3, v12, 1
	s_add_u32 s12, s27, s4
	global_load_lds_dwordx4 v128, s[20:21]
	s_addc_u32 s13, s28, s5
	s_mov_b32 m0, s11
	s_add_i32 s34, s11, 0x2000
	global_load_lds_dwordx4 v154, s[12:13]
	s_mov_b32 m0, s34
	s_add_u32 s4, s20, 0x40000
	global_load_lds_dwordx4 v128, s[12:13]
	s_addc_u32 s5, s21, 0
	s_add_i32 m0, s11, 0x14000
	v_mov_b32_e32 v129, v155
	global_load_lds_dwordx4 v154, s[4:5]
	s_add_i32 m0, s11, 0x16000
	s_mov_b32 s89, s59
	global_load_lds_dwordx4 v128, s[4:5]
	s_add_u32 s4, s12, 0x40000
	s_addc_u32 s5, s13, 0
	s_add_i32 s35, s11, 0x4000
	s_mov_b32 m0, s35
	s_add_i32 s36, s11, 0x6000
	global_load_lds_dwordx4 v154, s[4:5]
	s_mov_b32 m0, s36
	s_mov_b64 s[70:71], s[82:83]
	global_load_lds_dwordx4 v128, s[4:5]
	v_lshl_add_u64 v[6:7], s[20:21], 0, v[154:155]
	v_lshl_add_u64 v[4:5], s[20:21], 0, v[128:129]
	v_lshl_add_u64 v[2:3], s[12:13], 0, v[154:155]
	s_cmp_lg_u32 s2, 1
	v_lshl_add_u64 v[0:1], s[12:13], 0, v[128:129]
	s_cbranch_scc1 .LBB0_143
	s_barrier

;     __device__ __forceinline__ bool next(int i, Unit& u) const { if (i >= 4) return false; u.pm = pm; u.pn = i; return true; }
;     __device__ __forceinline__ bool next(int i, Unit& u) const {
;         const long L = (long)i * G + c; if (L >= nwg) return false;
;         int wgid = (int)L; { const int q = nwg / NXCD, r = nwg % NXCD, xcd = wgid % NXCD, off = wgid / NXCD; wgid = (xcd < r ? xcd * (q + 1) : r * (q + 1) + (xcd - r) * q) + off; }
;         const int nig = WGM * nN, gid = wgid / nig, fm = gid * WGM, gsz = (nM - fm) < WGM ? (nM - fm) : WGM;
;         u.pm = fm + ((wgid % nig) % gsz); u.pn = (wgid % nig) / gsz; return true;
.LBB0_149:
	s_ashr_i32 s0, s2, 3
	s_add_i32 s0, s8, s0
	s_xor_b32 s0, s0, 0x7f
	s_ashr_i32 s1, s0, 31
	s_lshr_b32 s1, s1, 27
	s_add_i32 s1, s0, s1
	s_ashr_i32 s2, s1, 5
	s_lshl_b32 s2, s2, 3
	s_sub_i32 s3, 0x100, s2
	s_min_i32 s3, s3, 8
	s_abs_i32 s8, s3
	v_cvt_f32_u32_e32 v0, s8
	s_sub_i32 s22, 0, s8
	s_andn2_b32 s1, s1, 31
	s_sub_i32 s1, s0, s1
	v_rcp_iflag_f32_e32 v0, v0
	s_abs_i32 s0, s1
	s_xor_b32 s9, s1, s3
	s_ashr_i32 s9, s9, 31
	v_mul_f32_e32 v0, 0x4f7ffffe, v0
	v_cvt_u32_f32_e32 v0, v0
	s_nop 0
	v_readfirstlane_b32 s23, v0
	s_mul_i32 s22, s22, s23
	s_mul_hi_u32 s22, s23, s22
	s_add_i32 s23, s23, s22
	s_mul_hi_u32 s22, s0, s23
	s_mul_i32 s23, s22, s8
	s_sub_i32 s0, s0, s23
	s_add_i32 s24, s22, 1
	s_sub_i32 s23, s0, s8
	s_cmp_ge_u32 s0, s8
	s_cselect_b32 s22, s24, s22
	s_cselect_b32 s0, s23, s0
	s_add_i32 s23, s22, 1
	s_cmp_ge_u32 s0, s8
	s_cselect_b32 s0, s23, s22
	s_xor_b32 s0, s0, s9
	s_sub_i32 s0, s0, s9
	s_mul_i32 s3, s0, s3
	s_sub_i32 s1, s1, s3
	s_add_i32 s2, s2, s1
